# speedup vs baseline: 1.0339x; 1.0021x over previous
; #define SCAN_LOAD(R, TOKP) do { const float* _p = (TOKP); \
;     R##nk = *(const f32x4*)(_p + opoff); R##w = *(const f32x4*)(_p + 64 + opoff); R##b = *(const f32x4*)(_p + 128 + opoff); \
;     R##k = *(const f32x4*)(_p + 192 + opoff); R##r = *(const f32x4*)(_p + 256 + opoff); R##v = _p[voff]; } while (0)
; __device__ __forceinline__ void scan_block(const int WV, const Params& P, int layer, int bh, int hv) {
;     ...
;   auto issue = [&](int chunk) {
;     size_t t = tbase + (size_t)chunk * SCH + htok;
;     const u16* zr = z + t * DIN + hch;
;     size_t ri = t * 1024 + hch;
;     Lr = *(const unsigned*)zr; Lk = *(const unsigned*)(zr + 1024); Lv = z[t * DIN + 2048 + hrow];
;     Lw = *(const unsigned*)(rwW + ri); Lkk = *(const unsigned*)(rwKK + ri); Lb = *(const unsigned*)(rwB + ri);
;     Lgn = rwG[t * 1024 + hrow];
;   };
;     ...
;   for (int chunk = 0; chunk < NCH; ++chunk) {
;     const int buf = chunk & 1;
;     if (chunk + 1 < NCH) { commit(buf ^ 1); Lg1 = Lgn; }
;     if (chunk + 2 < NCH) {
;       if (!prep_all_done && ((chunk + 2) >> 1) >= next_check) {
;         if (__hip_atomic_load((const gu32*)pdone_s, __ATOMIC_RELAXED, __HIP_MEMORY_SCOPE_AGENT) >= gridDim.x - 64) {
;           __builtin_amdgcn_fence(__ATOMIC_ACQUIRE, "agent");
;           prep_all_done = true;
;         } else {
;           const int t0w = (chunk + 2) >> 1;
;           wait_flags16(tflag + t0w, min(64, 512 - t0w), lane);
;           next_check = t0w + 64;
;         }
;       }
;       issue(chunk + 2);
;     }
;     if (chunk >= 1) prefetch_partner(chunk - 1);
;     {
;       const float* base = ring + (size_t)buf * SCH * 384;
;       float* yb = ypart + (size_t)buf * (SCH * 512) + yoff;
;       f32x4 Ank, Aw, Ab, Ak, Ar, Bnk, Bw, Bb, Bk, Br; float Av, Bv;
;       SCAN_LOAD(A, base);
; #pragma unroll 2
;       for (int tok = 0; tok < SCH; tok += 2) {
;         SCAN_LOAD(B, base + (tok + 1) * 384);
;         SCAN_STEP(A, yb + tok * 512);
;         SCAN_LOAD(A, base + ((tok + 2) & (SCH - 1)) * 384);
;         SCAN_STEP(B, yb + (tok + 1) * 512);
;       }
;     }
.LBB0_295:
.LBB0_296:
	s_not_b32 s20, s22
	s_lshl_b32 s20, s20, 8
	s_and_b32 s20, s20, 0x100
	s_mov_b32 s21, 0
	v_lshl_add_u64 v[254:255], v[26:27], 0, s[20:21]
	s_mul_i32 s13, s23, 0x6000
	v_lshl_or_b32 v18, v53, 2, s13
	ds_read_b128 v[2:5], v18
	ds_read_b128 v[6:9], v18 offset:256
	ds_read_b128 v[10:13], v18 offset:512
	ds_read_b128 v[14:17], v18 offset:768
	v_lshl_add_u32 v74, v56, 2, s13
	ds_read_b128 v[18:21], v18 offset:1024
	ds_read_b32 v210, v74 offset:1280
	v_cndmask_b32_e64 v73, 0, 1, s[8:9]
	v_mul_lo_u32 v74, v73, s79
	v_lshl_add_u32 v72, v73, 15, v57
	v_add_u32_e32 v73, v58, v74
	v_or_b32_e32 v74, v59, v74
	s_mov_b32 s20, -2
.LBB0_297:
	s_cmpk_gt_u32 s22, 0x3fd
	s_cbranch_scc1 .Liss_skip
	s_add_i32 s80, s22, 2
	s_lshl_b32 s80, s80, 4
	v_lshl_add_u64 v[242:243], v[34:35], 0, s[80:81]
	v_mov_b64_e32 v[244:245], s[46:47]
	v_mad_u64_u32 v[244:245], s[6:7], v242, s90, v[244:245]
	v_mad_i32_i24 v245, v243, s90, v245
	v_lshl_add_u64 v[246:247], v[244:245], 0, v[0:1]
	global_load_dword v64, v[246:247], off
	global_load_dword v65, v[246:247], off offset:2048
	v_lshlrev_b32_e32 v246, 1, v22
	v_mov_b32_e32 v247, v1
	v_lshl_add_u64 v[244:245], v[244:245], 0, v[246:247]
	v_add_co_u32_e32 v244, vcc, s36, v244
	v_lshlrev_b64 v[242:243], 11, v[242:243]
	s_nop 0
	v_addc_co_u32_e32 v245, vcc, 0, v245, vcc
	global_load_ushort v66, v[244:245], off
	v_or_b32_e32 v244, v242, v0
	v_mov_b32_e32 v245, v243
	v_lshl_add_u64 v[246:247], s[62:63], 0, v[244:245]
	global_load_dword v67, v[246:247], off
	v_lshl_add_u64 v[246:247], s[64:65], 0, v[244:245]
	v_lshl_add_u64 v[244:245], s[66:67], 0, v[244:245]
	v_lshl_add_u64 v[242:243], v[38:39], 0, v[242:243]
	global_load_dword v68, v[246:247], off
	global_load_dword v69, v[244:245], off
	global_load_ushort v70, v[242:243], off
.Liss_skip:
	ds_read_b128 v[76:79], v74
	ds_read_b128 v[80:83], v74 offset:256
	ds_read_b128 v[84:87], v74 offset:512
	ds_read_b128 v[88:91], v74 offset:768
	ds_read_b128 v[92:95], v74 offset:1024
	ds_read_b32 v96, v73
	s_waitcnt lgkmcnt(6)
	v_pk_mul_f32 v[98:99], v[60:61], v[2:3]
	v_pk_fma_f32 v[98:99], v[62:63], v[4:5], v[98:99]
	v_pk_mul_f32 v[100:101], v[60:61], v[6:7]
	v_add_f32_e32 v98, v98, v99
	v_pk_mul_f32 v[208:209], v[62:63], v[8:9]
	v_pk_fma_f32 v[100:101], v[210:211], v[14:15], v[100:101] op_sel_hi:[0,1,1]
	v_add_f32_dpp v98, v98, v98 row_ror:8 row_mask:0xf bank_mask:0xf
	v_pk_fma_f32 v[208:209], v[210:211], v[16:17], v[208:209] op_sel_hi:[0,1,1]
	ds_read_b128 v[212:215], v74 offset:1536
	v_add_f32_dpp v98, v98, v98 row_ror:4 row_mask:0xf bank_mask:0xf
	ds_read_b128 v[216:219], v74 offset:1792
	ds_read_b128 v[220:223], v74 offset:2048
	v_add_f32_dpp v98, v98, v98 row_ror:2 row_mask:0xf bank_mask:0xf
	ds_read_b128 v[224:227], v74 offset:2304
	ds_read_b128 v[228:231], v74 offset:2560
	v_add_f32_dpp v98, v98, v98 row_ror:1 row_mask:0xf bank_mask:0xf
	v_pk_fma_f32 v[60:61], v[98:99], v[10:11], v[100:101] op_sel_hi:[0,1,1]
	v_pk_fma_f32 v[62:63], v[98:99], v[12:13], v[208:209] op_sel_hi:[0,1,1]
	ds_read_b32 v232, v73 offset:1536
	v_pk_mul_f32 v[100:101], v[60:61], v[18:19]
	v_pk_fma_f32 v[100:101], v[62:63], v[20:21], v[100:101]
	s_nop 0
	v_add_f32_e32 v102, v100, v101
	ds_write_b32 v72, v102
	s_waitcnt lgkmcnt(7)
	v_pk_mul_f32 v[98:99], v[60:61], v[76:77]
	v_pk_fma_f32 v[98:99], v[62:63], v[78:79], v[98:99]
	v_pk_mul_f32 v[100:101], v[60:61], v[80:81]
	v_add_f32_e32 v98, v98, v99
	v_pk_mul_f32 v[208:209], v[62:63], v[82:83]
	v_pk_fma_f32 v[100:101], v[96:97], v[88:89], v[100:101] op_sel_hi:[0,1,1]
	v_add_f32_dpp v98, v98, v98 row_ror:8 row_mask:0xf bank_mask:0xf
	v_pk_fma_f32 v[208:209], v[96:97], v[90:91], v[208:209] op_sel_hi:[0,1,1]
	ds_read_b128 v[2:5], v74 offset:3072
	v_add_f32_dpp v98, v98, v98 row_ror:4 row_mask:0xf bank_mask:0xf
	ds_read_b128 v[6:9], v74 offset:3328
	ds_read_b128 v[10:13], v74 offset:3584
	v_add_f32_dpp v98, v98, v98 row_ror:2 row_mask:0xf bank_mask:0xf
	ds_read_b128 v[14:17], v74 offset:3840
	ds_read_b128 v[18:21], v74 offset:4096
	v_add_f32_dpp v98, v98, v98 row_ror:1 row_mask:0xf bank_mask:0xf
	v_pk_fma_f32 v[60:61], v[98:99], v[84:85], v[100:101] op_sel_hi:[0,1,1]
	v_pk_fma_f32 v[62:63], v[98:99], v[86:87], v[208:209] op_sel_hi:[0,1,1]
	ds_read_b32 v210, v73 offset:3072
	v_pk_mul_f32 v[100:101], v[60:61], v[92:93]
	v_pk_fma_f32 v[100:101], v[62:63], v[94:95], v[100:101]
	s_nop 0
	v_add_f32_e32 v102, v100, v101
	ds_write_b32 v72, v102 offset:2048
	s_waitcnt lgkmcnt(8)
	v_pk_mul_f32 v[98:99], v[60:61], v[212:213]
	v_pk_fma_f32 v[98:99], v[62:63], v[214:215], v[98:99]
	v_pk_mul_f32 v[100:101], v[60:61], v[216:217]
	v_add_f32_e32 v98, v98, v99
	v_pk_mul_f32 v[208:209], v[62:63], v[218:219]
	v_pk_fma_f32 v[100:101], v[232:233], v[224:225], v[100:101] op_sel_hi:[0,1,1]
	v_add_f32_dpp v98, v98, v98 row_ror:8 row_mask:0xf bank_mask:0xf
	v_pk_fma_f32 v[208:209], v[232:233], v[226:227], v[208:209] op_sel_hi:[0,1,1]
	ds_read_b128 v[76:79], v74 offset:4608
	v_add_f32_dpp v98, v98, v98 row_ror:4 row_mask:0xf bank_mask:0xf
	ds_read_b128 v[80:83], v74 offset:4864
	ds_read_b128 v[84:87], v74 offset:5120
	v_add_f32_dpp v98, v98, v98 row_ror:2 row_mask:0xf bank_mask:0xf
	ds_read_b128 v[88:91], v74 offset:5376
	ds_read_b128 v[92:95], v74 offset:5632
	v_add_f32_dpp v98, v98, v98 row_ror:1 row_mask:0xf bank_mask:0xf
	v_pk_fma_f32 v[60:61], v[98:99], v[220:221], v[100:101] op_sel_hi:[0,1,1]
	v_pk_fma_f32 v[62:63], v[98:99], v[222:223], v[208:209] op_sel_hi:[0,1,1]
	ds_read_b32 v96, v73 offset:4608
	v_pk_mul_f32 v[100:101], v[60:61], v[228:229]
	v_pk_fma_f32 v[100:101], v[62:63], v[230:231], v[100:101]
	s_nop 0
	v_add_f32_e32 v102, v100, v101
	ds_write_b32 v72, v102 offset:4096
	s_waitcnt lgkmcnt(8)
; #define SCAN_LOAD(R, TOKP) do { const float* _p = (TOKP); \
;     R##nk = *(const f32x4*)(_p + opoff); R##w = *(const f32x4*)(_p + 64 + opoff); R##b = *(const f32x4*)(_p + 128 + opoff); \
;     R##k = *(const f32x4*)(_p + 192 + opoff); R##r = *(const f32x4*)(_p + 256 + opoff); R##v = _p[voff]; } while (0)
; __device__ __forceinline__ void scan_block(const int WV, const Params& P, int layer, int bh, int hv) {
;     ...
; #pragma unroll 2
;       for (int tok = 0; tok < SCH; tok += 2) {
;         SCAN_LOAD(B, base + (tok + 1) * 384);
;         SCAN_STEP(A, yb + tok * 512);
;         SCAN_LOAD(A, base + ((tok + 2) & (SCH - 1)) * 384);
;         SCAN_STEP(B, yb + (tok + 1) * 512);
;       }
	v_pk_mul_f32 v[98:99], v[60:61], v[2:3]
	v_pk_fma_f32 v[98:99], v[62:63], v[4:5], v[98:99]
	v_pk_mul_f32 v[100:101], v[60:61], v[6:7]
	v_add_f32_e32 v98, v98, v99
	v_pk_mul_f32 v[208:209], v[62:63], v[8:9]
	v_pk_fma_f32 v[100:101], v[210:211], v[14:15], v[100:101] op_sel_hi:[0,1,1]
	v_add_f32_dpp v98, v98, v98 row_ror:8 row_mask:0xf bank_mask:0xf
	v_pk_fma_f32 v[208:209], v[210:211], v[16:17], v[208:209] op_sel_hi:[0,1,1]
	ds_read_b128 v[212:215], v74 offset:6144
	v_add_f32_dpp v98, v98, v98 row_ror:4 row_mask:0xf bank_mask:0xf
	ds_read_b128 v[216:219], v74 offset:6400
	ds_read_b128 v[220:223], v74 offset:6656
	v_add_f32_dpp v98, v98, v98 row_ror:2 row_mask:0xf bank_mask:0xf
	ds_read_b128 v[224:227], v74 offset:6912
	ds_read_b128 v[228:231], v74 offset:7168
	v_add_f32_dpp v98, v98, v98 row_ror:1 row_mask:0xf bank_mask:0xf
	v_pk_fma_f32 v[60:61], v[98:99], v[10:11], v[100:101] op_sel_hi:[0,1,1]
	v_pk_fma_f32 v[62:63], v[98:99], v[12:13], v[208:209] op_sel_hi:[0,1,1]
	ds_read_b32 v232, v73 offset:6144
	v_pk_mul_f32 v[100:101], v[60:61], v[18:19]
	v_pk_fma_f32 v[100:101], v[62:63], v[20:21], v[100:101]
	s_nop 0
	v_add_f32_e32 v102, v100, v101
	ds_write_b32 v72, v102 offset:6144
	s_waitcnt lgkmcnt(8)
	v_pk_mul_f32 v[98:99], v[60:61], v[76:77]
	v_pk_fma_f32 v[98:99], v[62:63], v[78:79], v[98:99]
	v_pk_mul_f32 v[100:101], v[60:61], v[80:81]
	v_add_f32_e32 v98, v98, v99
	v_pk_mul_f32 v[208:209], v[62:63], v[82:83]
	v_pk_fma_f32 v[100:101], v[96:97], v[88:89], v[100:101] op_sel_hi:[0,1,1]
	v_add_f32_dpp v98, v98, v98 row_ror:8 row_mask:0xf bank_mask:0xf
	v_pk_fma_f32 v[208:209], v[96:97], v[90:91], v[208:209] op_sel_hi:[0,1,1]
	ds_read_b128 v[2:5], v74 offset:7680
	v_add_f32_dpp v98, v98, v98 row_ror:4 row_mask:0xf bank_mask:0xf
	ds_read_b128 v[6:9], v74 offset:7936
	ds_read_b128 v[10:13], v74 offset:8192
	v_add_f32_dpp v98, v98, v98 row_ror:2 row_mask:0xf bank_mask:0xf
	ds_read_b128 v[14:17], v74 offset:8448
	ds_read_b128 v[18:21], v74 offset:8704
	v_add_f32_dpp v98, v98, v98 row_ror:1 row_mask:0xf bank_mask:0xf
	v_pk_fma_f32 v[60:61], v[98:99], v[84:85], v[100:101] op_sel_hi:[0,1,1]
	v_pk_fma_f32 v[62:63], v[98:99], v[86:87], v[208:209] op_sel_hi:[0,1,1]
	ds_read_b32 v210, v73 offset:7680
	v_pk_mul_f32 v[100:101], v[60:61], v[92:93]
	v_pk_fma_f32 v[100:101], v[62:63], v[94:95], v[100:101]
	s_nop 0
	v_add_f32_e32 v102, v100, v101
	ds_write_b32 v72, v102 offset:8192
	s_waitcnt lgkmcnt(8)
	v_pk_mul_f32 v[98:99], v[60:61], v[212:213]
	v_pk_fma_f32 v[98:99], v[62:63], v[214:215], v[98:99]
	v_pk_mul_f32 v[100:101], v[60:61], v[216:217]
	v_add_f32_e32 v98, v98, v99
	v_pk_mul_f32 v[208:209], v[62:63], v[218:219]
	v_pk_fma_f32 v[100:101], v[232:233], v[224:225], v[100:101] op_sel_hi:[0,1,1]
	v_add_f32_dpp v98, v98, v98 row_ror:8 row_mask:0xf bank_mask:0xf
	v_pk_fma_f32 v[208:209], v[232:233], v[226:227], v[208:209] op_sel_hi:[0,1,1]
	ds_read_b128 v[76:79], v74 offset:9216
	v_add_f32_dpp v98, v98, v98 row_ror:4 row_mask:0xf bank_mask:0xf
	ds_read_b128 v[80:83], v74 offset:9472
	ds_read_b128 v[84:87], v74 offset:9728
	v_add_f32_dpp v98, v98, v98 row_ror:2 row_mask:0xf bank_mask:0xf
	ds_read_b128 v[88:91], v74 offset:9984
	ds_read_b128 v[92:95], v74 offset:10240
	v_add_f32_dpp v98, v98, v98 row_ror:1 row_mask:0xf bank_mask:0xf
	v_pk_fma_f32 v[60:61], v[98:99], v[220:221], v[100:101] op_sel_hi:[0,1,1]
	v_pk_fma_f32 v[62:63], v[98:99], v[222:223], v[208:209] op_sel_hi:[0,1,1]
	ds_read_b32 v96, v73 offset:9216
	v_pk_mul_f32 v[100:101], v[60:61], v[228:229]
	v_pk_fma_f32 v[100:101], v[62:63], v[230:231], v[100:101]
	s_nop 0
	v_add_f32_e32 v102, v100, v101
	ds_write_b32 v72, v102 offset:10240
	s_waitcnt lgkmcnt(8)
	v_pk_mul_f32 v[98:99], v[60:61], v[2:3]
	v_pk_fma_f32 v[98:99], v[62:63], v[4:5], v[98:99]
	v_pk_mul_f32 v[100:101], v[60:61], v[6:7]
	v_add_f32_e32 v98, v98, v99
	v_pk_mul_f32 v[208:209], v[62:63], v[8:9]
	v_pk_fma_f32 v[100:101], v[210:211], v[14:15], v[100:101] op_sel_hi:[0,1,1]
	v_add_f32_dpp v98, v98, v98 row_ror:8 row_mask:0xf bank_mask:0xf
	v_pk_fma_f32 v[208:209], v[210:211], v[16:17], v[208:209] op_sel_hi:[0,1,1]
	ds_read_b128 v[212:215], v74 offset:10752
	v_add_f32_dpp v98, v98, v98 row_ror:4 row_mask:0xf bank_mask:0xf
	ds_read_b128 v[216:219], v74 offset:11008
	ds_read_b128 v[220:223], v74 offset:11264
	v_add_f32_dpp v98, v98, v98 row_ror:2 row_mask:0xf bank_mask:0xf
	ds_read_b128 v[224:227], v74 offset:11520
	ds_read_b128 v[228:231], v74 offset:11776
	v_add_f32_dpp v98, v98, v98 row_ror:1 row_mask:0xf bank_mask:0xf
	v_pk_fma_f32 v[60:61], v[98:99], v[10:11], v[100:101] op_sel_hi:[0,1,1]
	v_pk_fma_f32 v[62:63], v[98:99], v[12:13], v[208:209] op_sel_hi:[0,1,1]
	ds_read_b32 v232, v73 offset:10752
	v_pk_mul_f32 v[100:101], v[60:61], v[18:19]
	v_pk_fma_f32 v[100:101], v[62:63], v[20:21], v[100:101]
	s_nop 0
	v_add_f32_e32 v102, v100, v101
	ds_write_b32 v72, v102 offset:12288
	s_waitcnt lgkmcnt(8)
	v_pk_mul_f32 v[98:99], v[60:61], v[76:77]
	v_pk_fma_f32 v[98:99], v[62:63], v[78:79], v[98:99]
	v_pk_mul_f32 v[100:101], v[60:61], v[80:81]
	v_add_f32_e32 v98, v98, v99
	v_pk_mul_f32 v[208:209], v[62:63], v[82:83]
	v_pk_fma_f32 v[100:101], v[96:97], v[88:89], v[100:101] op_sel_hi:[0,1,1]
	v_add_f32_dpp v98, v98, v98 row_ror:8 row_mask:0xf bank_mask:0xf
	v_pk_fma_f32 v[208:209], v[96:97], v[90:91], v[208:209] op_sel_hi:[0,1,1]
	ds_read_b128 v[2:5], v74 offset:12288
	v_add_f32_dpp v98, v98, v98 row_ror:4 row_mask:0xf bank_mask:0xf
	ds_read_b128 v[6:9], v74 offset:12544
	ds_read_b128 v[10:13], v74 offset:12800
	v_add_f32_dpp v98, v98, v98 row_ror:2 row_mask:0xf bank_mask:0xf
	ds_read_b128 v[14:17], v74 offset:13056
	ds_read_b128 v[18:21], v74 offset:13312
	v_add_f32_dpp v98, v98, v98 row_ror:1 row_mask:0xf bank_mask:0xf
	v_pk_fma_f32 v[60:61], v[98:99], v[84:85], v[100:101] op_sel_hi:[0,1,1]
	v_pk_fma_f32 v[62:63], v[98:99], v[86:87], v[208:209] op_sel_hi:[0,1,1]
	ds_read_b32 v210, v73 offset:12288
	v_pk_mul_f32 v[100:101], v[60:61], v[92:93]
	v_pk_fma_f32 v[100:101], v[62:63], v[94:95], v[100:101]
	s_nop 0
	v_add_f32_e32 v102, v100, v101
	ds_write_b32 v72, v102 offset:14336
	s_waitcnt lgkmcnt(8)
; __device__ __forceinline__ void scan_block(const int WV, const Params& P, int layer, int bh, int hv) {
;     ...
;   auto prefetch_partner = [&](int chunk) {
;     const int slot = (chunk & 1) * (SCH * 2);
;     pg1 = __hip_atomic_load(xpart + slot, __ATOMIC_RELAXED, __HIP_MEMORY_SCOPE_AGENT);
;     pg2 = __hip_atomic_load(xpart + slot + 1, __ATOMIC_RELAXED, __HIP_MEMORY_SCOPE_AGENT);
;   };
	v_pk_mul_f32 v[98:99], v[60:61], v[212:213]
	v_pk_fma_f32 v[98:99], v[62:63], v[214:215], v[98:99]
	v_pk_mul_f32 v[100:101], v[60:61], v[216:217]
	v_add_f32_e32 v98, v98, v99
	v_pk_mul_f32 v[208:209], v[62:63], v[218:219]
	v_pk_fma_f32 v[100:101], v[232:233], v[224:225], v[100:101] op_sel_hi:[0,1,1]
	v_add_f32_dpp v98, v98, v98 row_ror:8 row_mask:0xf bank_mask:0xf
	v_pk_fma_f32 v[208:209], v[232:233], v[226:227], v[208:209] op_sel_hi:[0,1,1]
	ds_read_b128 v[76:79], v74 offset:13824
	v_add_f32_dpp v98, v98, v98 row_ror:4 row_mask:0xf bank_mask:0xf
	ds_read_b128 v[80:83], v74 offset:14080
	ds_read_b128 v[84:87], v74 offset:14336
	v_add_f32_dpp v98, v98, v98 row_ror:2 row_mask:0xf bank_mask:0xf
	ds_read_b128 v[88:91], v74 offset:14592
	ds_read_b128 v[92:95], v74 offset:14848
	v_add_f32_dpp v98, v98, v98 row_ror:1 row_mask:0xf bank_mask:0xf
	v_pk_fma_f32 v[60:61], v[98:99], v[220:221], v[100:101] op_sel_hi:[0,1,1]
	v_pk_fma_f32 v[62:63], v[98:99], v[222:223], v[208:209] op_sel_hi:[0,1,1]
	ds_read_b32 v96, v73 offset:13824
	v_pk_mul_f32 v[100:101], v[60:61], v[228:229]
	v_pk_fma_f32 v[100:101], v[62:63], v[230:231], v[100:101]
	s_nop 0
	v_add_f32_e32 v102, v100, v101
	ds_write_b32 v72, v102 offset:16384
	s_waitcnt lgkmcnt(8)
	v_pk_mul_f32 v[98:99], v[60:61], v[2:3]
	v_pk_fma_f32 v[98:99], v[62:63], v[4:5], v[98:99]
	v_pk_mul_f32 v[100:101], v[60:61], v[6:7]
	v_add_f32_e32 v98, v98, v99
	v_pk_mul_f32 v[208:209], v[62:63], v[8:9]
	v_pk_fma_f32 v[100:101], v[210:211], v[14:15], v[100:101] op_sel_hi:[0,1,1]
	v_add_f32_dpp v98, v98, v98 row_ror:8 row_mask:0xf bank_mask:0xf
	v_pk_fma_f32 v[208:209], v[210:211], v[16:17], v[208:209] op_sel_hi:[0,1,1]
	ds_read_b128 v[212:215], v74 offset:15360
	v_add_f32_dpp v98, v98, v98 row_ror:4 row_mask:0xf bank_mask:0xf
	ds_read_b128 v[216:219], v74 offset:15616
	ds_read_b128 v[220:223], v74 offset:15872
	v_add_f32_dpp v98, v98, v98 row_ror:2 row_mask:0xf bank_mask:0xf
	ds_read_b128 v[224:227], v74 offset:16128
	ds_read_b128 v[228:231], v74 offset:16384
	v_add_f32_dpp v98, v98, v98 row_ror:1 row_mask:0xf bank_mask:0xf
	v_pk_fma_f32 v[60:61], v[98:99], v[10:11], v[100:101] op_sel_hi:[0,1,1]
	v_pk_fma_f32 v[62:63], v[98:99], v[12:13], v[208:209] op_sel_hi:[0,1,1]
	ds_read_b32 v232, v73 offset:15360
	v_pk_mul_f32 v[100:101], v[60:61], v[18:19]
	v_pk_fma_f32 v[100:101], v[62:63], v[20:21], v[100:101]
	s_nop 0
	v_add_f32_e32 v102, v100, v101
	ds_write_b32 v72, v102 offset:18432
	s_waitcnt lgkmcnt(8)
	v_pk_mul_f32 v[98:99], v[60:61], v[76:77]
	v_pk_fma_f32 v[98:99], v[62:63], v[78:79], v[98:99]
	v_pk_mul_f32 v[100:101], v[60:61], v[80:81]
	v_add_f32_e32 v98, v98, v99
	v_pk_mul_f32 v[208:209], v[62:63], v[82:83]
	v_pk_fma_f32 v[100:101], v[96:97], v[88:89], v[100:101] op_sel_hi:[0,1,1]
	v_add_f32_dpp v98, v98, v98 row_ror:8 row_mask:0xf bank_mask:0xf
	v_pk_fma_f32 v[208:209], v[96:97], v[90:91], v[208:209] op_sel_hi:[0,1,1]
	ds_read_b128 v[2:5], v74 offset:16896
	v_add_f32_dpp v98, v98, v98 row_ror:4 row_mask:0xf bank_mask:0xf
	ds_read_b128 v[6:9], v74 offset:17152
	ds_read_b128 v[10:13], v74 offset:17408
	v_add_f32_dpp v98, v98, v98 row_ror:2 row_mask:0xf bank_mask:0xf
	ds_read_b128 v[14:17], v74 offset:17664
	ds_read_b128 v[18:21], v74 offset:17920
	v_add_f32_dpp v98, v98, v98 row_ror:1 row_mask:0xf bank_mask:0xf
	v_pk_fma_f32 v[60:61], v[98:99], v[84:85], v[100:101] op_sel_hi:[0,1,1]
	v_pk_fma_f32 v[62:63], v[98:99], v[86:87], v[208:209] op_sel_hi:[0,1,1]
	ds_read_b32 v210, v73 offset:16896
	v_pk_mul_f32 v[100:101], v[60:61], v[92:93]
	v_pk_fma_f32 v[100:101], v[62:63], v[94:95], v[100:101]
	s_nop 0
	v_add_f32_e32 v102, v100, v101
	ds_write_b32 v72, v102 offset:20480
	s_waitcnt lgkmcnt(8)
	v_pk_mul_f32 v[98:99], v[60:61], v[212:213]
	v_pk_fma_f32 v[98:99], v[62:63], v[214:215], v[98:99]
	v_pk_mul_f32 v[100:101], v[60:61], v[216:217]
	v_add_f32_e32 v98, v98, v99
	v_pk_mul_f32 v[208:209], v[62:63], v[218:219]
	v_pk_fma_f32 v[100:101], v[232:233], v[224:225], v[100:101] op_sel_hi:[0,1,1]
	v_add_f32_dpp v98, v98, v98 row_ror:8 row_mask:0xf bank_mask:0xf
	v_pk_fma_f32 v[208:209], v[232:233], v[226:227], v[208:209] op_sel_hi:[0,1,1]
	ds_read_b128 v[76:79], v74 offset:18432
	v_add_f32_dpp v98, v98, v98 row_ror:4 row_mask:0xf bank_mask:0xf
	ds_read_b128 v[80:83], v74 offset:18688
	ds_read_b128 v[84:87], v74 offset:18944
	v_add_f32_dpp v98, v98, v98 row_ror:2 row_mask:0xf bank_mask:0xf
	ds_read_b128 v[88:91], v74 offset:19200
	ds_read_b128 v[92:95], v74 offset:19456
	v_add_f32_dpp v98, v98, v98 row_ror:1 row_mask:0xf bank_mask:0xf
	v_pk_fma_f32 v[60:61], v[98:99], v[220:221], v[100:101] op_sel_hi:[0,1,1]
	v_pk_fma_f32 v[62:63], v[98:99], v[222:223], v[208:209] op_sel_hi:[0,1,1]
	ds_read_b32 v96, v73 offset:18432
	v_pk_mul_f32 v[100:101], v[60:61], v[228:229]
	v_pk_fma_f32 v[100:101], v[62:63], v[230:231], v[100:101]
	s_nop 0
	v_add_f32_e32 v102, v100, v101
	ds_write_b32 v72, v102 offset:22528
	global_load_dwordx2 v[42:43], v[254:255], off sc1
	global_load_dwordx2 v[44:45], v[254:255], off offset:8 sc1
	s_waitcnt lgkmcnt(8)
; #define LDS_BARRIER() do { asm volatile("s_waitcnt lgkmcnt(0)" ::: "memory"); __builtin_amdgcn_s_barrier(); asm volatile("" ::: "memory"); } while (0)
; #define SCAN_LOAD(R, TOKP) do { const float* _p = (TOKP); \
;     R##nk = *(const f32x4*)(_p + opoff); R##w = *(const f32x4*)(_p + 64 + opoff); R##b = *(const f32x4*)(_p + 128 + opoff); \
;     R##k = *(const f32x4*)(_p + 192 + opoff); R##r = *(const f32x4*)(_p + 256 + opoff); R##v = _p[voff]; } while (0)
; __device__ __forceinline__ void scan_block(const int WV, const Params& P, int layer, int bh, int hv) {
;     ...
; #pragma unroll 2
;       for (int tok = 0; tok < SCH; tok += 2) {
;         SCAN_LOAD(B, base + (tok + 1) * 384);
;         SCAN_STEP(A, yb + tok * 512);
;         SCAN_LOAD(A, base + ((tok + 2) & (SCH - 1)) * 384);
;         SCAN_STEP(B, yb + (tok + 1) * 512);
;       }
;     }
;     LDS_BARRIER();
;     if (chunk >= 1) post_b(chunk - 1, (unsigned)(layer * 2048 + chunk));
	v_pk_mul_f32 v[98:99], v[60:61], v[2:3]
	v_pk_fma_f32 v[98:99], v[62:63], v[4:5], v[98:99]
	v_pk_mul_f32 v[100:101], v[60:61], v[6:7]
	v_add_f32_e32 v98, v98, v99
	v_pk_mul_f32 v[208:209], v[62:63], v[8:9]
	v_pk_fma_f32 v[100:101], v[210:211], v[14:15], v[100:101] op_sel_hi:[0,1,1]
	v_add_f32_dpp v98, v98, v98 row_ror:8 row_mask:0xf bank_mask:0xf
	v_pk_fma_f32 v[208:209], v[210:211], v[16:17], v[208:209] op_sel_hi:[0,1,1]
	ds_read_b128 v[212:215], v74 offset:19968
	v_add_f32_dpp v98, v98, v98 row_ror:4 row_mask:0xf bank_mask:0xf
	ds_read_b128 v[216:219], v74 offset:20224
	ds_read_b128 v[220:223], v74 offset:20480
	v_add_f32_dpp v98, v98, v98 row_ror:2 row_mask:0xf bank_mask:0xf
	ds_read_b128 v[224:227], v74 offset:20736
	ds_read_b128 v[228:231], v74 offset:20992
	v_add_f32_dpp v98, v98, v98 row_ror:1 row_mask:0xf bank_mask:0xf
	v_pk_fma_f32 v[60:61], v[98:99], v[10:11], v[100:101] op_sel_hi:[0,1,1]
	v_pk_fma_f32 v[62:63], v[98:99], v[12:13], v[208:209] op_sel_hi:[0,1,1]
	ds_read_b32 v232, v73 offset:19968
	v_pk_mul_f32 v[100:101], v[60:61], v[18:19]
	v_pk_fma_f32 v[100:101], v[62:63], v[20:21], v[100:101]
	s_nop 0
	v_add_f32_e32 v102, v100, v101
	ds_write_b32 v72, v102 offset:24576
	s_waitcnt lgkmcnt(8)
	v_pk_mul_f32 v[98:99], v[60:61], v[76:77]
	v_pk_fma_f32 v[98:99], v[62:63], v[78:79], v[98:99]
	v_pk_mul_f32 v[100:101], v[60:61], v[80:81]
	v_add_f32_e32 v98, v98, v99
	v_pk_mul_f32 v[208:209], v[62:63], v[82:83]
	v_pk_fma_f32 v[100:101], v[96:97], v[88:89], v[100:101] op_sel_hi:[0,1,1]
	v_add_f32_dpp v98, v98, v98 row_ror:8 row_mask:0xf bank_mask:0xf
	v_pk_fma_f32 v[208:209], v[96:97], v[90:91], v[208:209] op_sel_hi:[0,1,1]
	ds_read_b128 v[2:5], v74 offset:21504
	v_add_f32_dpp v98, v98, v98 row_ror:4 row_mask:0xf bank_mask:0xf
	ds_read_b128 v[6:9], v74 offset:21760
	ds_read_b128 v[10:13], v74 offset:22016
	v_add_f32_dpp v98, v98, v98 row_ror:2 row_mask:0xf bank_mask:0xf
	ds_read_b128 v[14:17], v74 offset:22272
	ds_read_b128 v[18:21], v74 offset:22528
	v_add_f32_dpp v98, v98, v98 row_ror:1 row_mask:0xf bank_mask:0xf
	v_pk_fma_f32 v[60:61], v[98:99], v[84:85], v[100:101] op_sel_hi:[0,1,1]
	v_pk_fma_f32 v[62:63], v[98:99], v[86:87], v[208:209] op_sel_hi:[0,1,1]
	ds_read_b32 v210, v73 offset:21504
	v_pk_mul_f32 v[100:101], v[60:61], v[92:93]
	v_pk_fma_f32 v[100:101], v[62:63], v[94:95], v[100:101]
	s_nop 0
	v_add_f32_e32 v102, v100, v101
	ds_write_b32 v72, v102 offset:26624
	s_waitcnt lgkmcnt(8)
	v_pk_mul_f32 v[98:99], v[60:61], v[212:213]
	v_pk_fma_f32 v[98:99], v[62:63], v[214:215], v[98:99]
	v_pk_mul_f32 v[100:101], v[60:61], v[216:217]
	v_add_f32_e32 v98, v98, v99
	v_pk_mul_f32 v[208:209], v[62:63], v[218:219]
	v_pk_fma_f32 v[100:101], v[232:233], v[224:225], v[100:101] op_sel_hi:[0,1,1]
	v_add_f32_dpp v98, v98, v98 row_ror:8 row_mask:0xf bank_mask:0xf
	v_pk_fma_f32 v[208:209], v[232:233], v[226:227], v[208:209] op_sel_hi:[0,1,1]
	s_nop 0
	v_add_f32_dpp v98, v98, v98 row_ror:4 row_mask:0xf bank_mask:0xf
	s_nop 1
	v_add_f32_dpp v98, v98, v98 row_ror:2 row_mask:0xf bank_mask:0xf
	s_nop 1
	v_add_f32_dpp v98, v98, v98 row_ror:1 row_mask:0xf bank_mask:0xf
	v_pk_fma_f32 v[60:61], v[98:99], v[220:221], v[100:101] op_sel_hi:[0,1,1]
	v_pk_fma_f32 v[62:63], v[98:99], v[222:223], v[208:209] op_sel_hi:[0,1,1]
	v_pk_mul_f32 v[100:101], v[60:61], v[228:229]
	v_pk_fma_f32 v[100:101], v[62:63], v[230:231], v[100:101]
	s_nop 0
	v_add_f32_e32 v102, v100, v101
	ds_write_b32 v72, v102 offset:28672
	s_waitcnt lgkmcnt(2)
	v_pk_mul_f32 v[98:99], v[60:61], v[2:3]
	v_pk_fma_f32 v[98:99], v[62:63], v[4:5], v[98:99]
	v_pk_mul_f32 v[100:101], v[60:61], v[6:7]
	v_add_f32_e32 v98, v98, v99
	v_pk_mul_f32 v[208:209], v[62:63], v[8:9]
	v_pk_fma_f32 v[100:101], v[210:211], v[14:15], v[100:101] op_sel_hi:[0,1,1]
	v_add_f32_dpp v98, v98, v98 row_ror:8 row_mask:0xf bank_mask:0xf
	v_pk_fma_f32 v[208:209], v[210:211], v[16:17], v[208:209] op_sel_hi:[0,1,1]
	s_nop 0
	v_add_f32_dpp v98, v98, v98 row_ror:4 row_mask:0xf bank_mask:0xf
	s_nop 1
	v_add_f32_dpp v98, v98, v98 row_ror:2 row_mask:0xf bank_mask:0xf
	s_nop 1
	v_add_f32_dpp v98, v98, v98 row_ror:1 row_mask:0xf bank_mask:0xf
	v_pk_fma_f32 v[60:61], v[98:99], v[10:11], v[100:101] op_sel_hi:[0,1,1]
	v_pk_fma_f32 v[62:63], v[98:99], v[12:13], v[208:209] op_sel_hi:[0,1,1]
	v_pk_mul_f32 v[100:101], v[60:61], v[18:19]
	v_pk_fma_f32 v[100:101], v[62:63], v[20:21], v[100:101]
	s_nop 0
	v_add_f32_e32 v102, v100, v101
	ds_write_b32 v72, v102 offset:30720
	s_cmp_eq_u32 s22, 0
	s_cbranch_scc1 .Lpb_skip
	s_add_i32 s80, s22, s31
	v_mov_b32_e32 v204, s80
